# out-proj epilogue: 16 four-lane ss atomics of the first 64-row half batched into one 64-lane 256-byte global_atomic_add_f32 (per-lane select by column group)
# speedup vs baseline: 1.0373x; 1.0003x over previous
; DI float bflo(unsigned v) { return __uint_as_float(v << 16); }
; DI float bfhi(unsigned v) { return __uint_as_float(v & 0xffff0000u); }
; template <int EPI>
; DI void gemm_tile(const Params& p, int layer, int mt, int nt, u16* sm, int wv) {
;     ...
;       for (int t = 0; t < 16; ++t) {
;         const int row = (lane >> 4) + 4 * t;
;         const f32x4 a4 = *(const f32x4*)(stg + row * 68 + kc * 4);
;         const float v0 = bflo(xb[t][0]) + a4[0], v1 = bfhi(xb[t][0]) + a4[1], v2 = bflo(xb[t][1]) + a4[2], v3 = bfhi(xb[t][1]) + a4[3];
;         float sq = v0 * v0 + v1 * v1 + v2 * v2 + v3 * v3;
;         u32x2 pv = {pk2(v0, v1), pk2(v2, v3)};
;         if (has_next) *(u32x2*)(xrow + (size_t)row * DM) = pv;
;         else *(u32x2*)(x2row + (size_t)row * DM) = pv;
;         sq += shx(sq, lane, 1); sq += shx(sq, lane, 2); sq += shx(sq, lane, 4); sq += shx(sq, lane, 8);
;         if (kc == 0) atomicAdd(ssn + mrow0 + row, sq);
.LBB0_403:
	v_and_b32_e32 v66, 63, v185
	v_lshlrev_b32_e32 v71, 2, v66
	v_pk_mul_f32 v[66:67], v[104:105], v[104:105]
	v_pk_mul_f32 v[104:105], v[136:137], v[136:137]
	v_add_f32_e32 v66, v66, v67
	v_add_f32_e32 v66, v104, v66
	v_xor_b32_e32 v138, 4, v71
	v_add_f32_e32 v66, v105, v66
	s_nop 1
	v_mov_b32_dpp v67, v66 quad_perm:[1,0,3,2] row_mask:0xf bank_mask:0xf
	v_xor_b32_e32 v137, 8, v71
	v_xor_b32_e32 v139, 16, v71
	v_xor_b32_e32 v136, 32, v71
	v_cmp_eq_u32_e64 s[36:37], 0, v180
	s_waitcnt lgkmcnt(0)
	v_add_f32_e32 v66, v66, v67
	s_nop 1
	v_mov_b32_dpp v67, v66 quad_perm:[2,3,0,1] row_mask:0xf bank_mask:0xf
	v_lshl_add_u64 v[104:105], v[68:69], 2, s[0:1]
	s_waitcnt lgkmcnt(0)
	v_add_f32_e32 v66, v66, v67
	s_nop 1
	v_mov_b32_dpp v67, v66 row_half_mirror row_mask:0xf bank_mask:0xf
	s_waitcnt lgkmcnt(0)
	v_add_f32_e32 v67, v66, v67
	s_nop 1
	v_mov_b32_dpp v71, v67 row_mirror row_mask:0xf bank_mask:0xf
	v_lshlrev_b32_e32 v66, 2, v183
	v_add_f32_e32 v146, v67, v71
	v_cmp_eq_u32_e64 s[4:5], 0, v180
	s_nop 1
	v_cndmask_b32_e64 v147, v147, v146, s[4:5]
.LBB0_405:
	v_mul_u32_u24_e32 v67, 0x110, v183
	v_add_u32_e32 v69, v67, v184
	ds_read_b128 v[140:143], v69 offset:1088
	v_lshlrev_b32_e32 v144, 16, v132
	v_and_b32_e32 v145, 0xffff0000, v132
	v_lshlrev_b32_e32 v132, 16, v133
	v_and_b32_e32 v133, 0xffff0000, v133
	s_waitcnt lgkmcnt(0)
	v_pk_add_f32 v[140:141], v[140:141], v[144:145]
	v_pk_add_f32 v[142:143], v[142:143], v[132:133]
	v_pk_mul_f32 v[132:133], v[140:141], v[140:141]
	v_pk_mul_f32 v[144:145], v[142:143], v[142:143]
	v_add_f32_e32 v67, v132, v133
	v_add_f32_e32 v67, v144, v67
	v_add_f32_e32 v67, v145, v67
	s_nop 1
	v_mov_b32_dpp v71, v67 quad_perm:[1,0,3,2] row_mask:0xf bank_mask:0xf
	v_or_b32_e32 v132, 4, v183
	v_cndmask_b32_e64 v111, v135, v111, s[34:35]
	v_cndmask_b32_e64 v110, v134, v110, s[34:35]
	v_lshlrev_b32_e32 v134, 11, v132
	s_waitcnt lgkmcnt(0)
	v_add_f32_e32 v67, v67, v71
	s_nop 1
	v_mov_b32_dpp v71, v67 quad_perm:[2,3,0,1] row_mask:0xf bank_mask:0xf
	v_mov_b32_e32 v135, v1
	v_cvt_pk_bf16_f32 v140, v140, v141
	v_cvt_pk_bf16_f32 v141, v142, v143
	v_lshl_add_u64 v[134:135], v[110:111], 0, v[134:135]
	s_waitcnt lgkmcnt(0)
	v_add_f32_e32 v67, v67, v71
	s_nop 1
	v_mov_b32_dpp v71, v67 row_half_mirror row_mask:0xf bank_mask:0xf
	global_store_dwordx2 v[134:135], v[140:141], off
	s_waitcnt lgkmcnt(0)
	v_add_f32_e32 v67, v67, v71
	s_nop 1
	v_mov_b32_dpp v71, v67 row_mirror row_mask:0xf bank_mask:0xf
	v_add_f32_e32 v146, v67, v71
	v_cmp_eq_u32_e64 s[4:5], 1, v180
	s_nop 1
	v_cndmask_b32_e64 v147, v147, v146, s[4:5]
.LBB0_407:
	ds_read_b128 v[140:143], v69 offset:2176
	v_lshlrev_b32_e32 v134, 16, v130
	v_and_b32_e32 v135, 0xffff0000, v130
	v_lshlrev_b32_e32 v130, 16, v131
	v_and_b32_e32 v131, 0xffff0000, v131
	s_waitcnt lgkmcnt(0)
	v_pk_add_f32 v[134:135], v[140:141], v[134:135]
	v_pk_add_f32 v[140:141], v[142:143], v[130:131]
	v_pk_mul_f32 v[130:131], v[134:135], v[134:135]
	v_pk_mul_f32 v[142:143], v[140:141], v[140:141]
	v_add_f32_e32 v67, v130, v131
	v_add_f32_e32 v67, v142, v67
	v_add_f32_e32 v67, v143, v67
	s_nop 1
	v_mov_b32_dpp v71, v67 quad_perm:[1,0,3,2] row_mask:0xf bank_mask:0xf
	v_or_b32_e32 v130, 8, v183
	v_cvt_pk_bf16_f32 v134, v134, v135
	v_cvt_pk_bf16_f32 v135, v140, v141
	v_lshlrev_b32_e32 v140, 11, v130
	s_waitcnt lgkmcnt(0)
	v_add_f32_e32 v67, v67, v71
	s_nop 1
	v_mov_b32_dpp v71, v67 quad_perm:[2,3,0,1] row_mask:0xf bank_mask:0xf
	v_mov_b32_e32 v141, v1
	v_lshl_add_u64 v[140:141], v[110:111], 0, v[140:141]
	global_store_dwordx2 v[140:141], v[134:135], off
	s_waitcnt lgkmcnt(0)
	v_add_f32_e32 v67, v67, v71
	s_nop 1
	v_mov_b32_dpp v71, v67 row_half_mirror row_mask:0xf bank_mask:0xf
	s_waitcnt lgkmcnt(0)
	v_add_f32_e32 v67, v67, v71
	s_nop 1
	v_mov_b32_dpp v71, v67 row_mirror row_mask:0xf bank_mask:0xf
	v_add_f32_e32 v146, v67, v71
	v_cmp_eq_u32_e64 s[4:5], 2, v180
	s_nop 1
	v_cndmask_b32_e64 v147, v147, v146, s[4:5]
.LBB0_409:
	ds_read_b128 v[140:143], v69 offset:3264
	v_lshlrev_b32_e32 v134, 16, v128
	v_and_b32_e32 v135, 0xffff0000, v128
	v_lshlrev_b32_e32 v128, 16, v129
	v_and_b32_e32 v129, 0xffff0000, v129
	s_waitcnt lgkmcnt(0)
	v_pk_add_f32 v[134:135], v[140:141], v[134:135]
	v_pk_add_f32 v[140:141], v[142:143], v[128:129]
	v_pk_mul_f32 v[128:129], v[134:135], v[134:135]
	v_pk_mul_f32 v[142:143], v[140:141], v[140:141]
	v_add_f32_e32 v67, v128, v129
	v_add_f32_e32 v67, v142, v67
	v_add_f32_e32 v67, v143, v67
	s_nop 1
	v_mov_b32_dpp v71, v67 quad_perm:[1,0,3,2] row_mask:0xf bank_mask:0xf
	v_or_b32_e32 v128, 12, v183
	v_cvt_pk_bf16_f32 v134, v134, v135
	v_cvt_pk_bf16_f32 v135, v140, v141
	v_lshlrev_b32_e32 v140, 11, v128
	s_waitcnt lgkmcnt(0)
	v_add_f32_e32 v67, v67, v71
	s_nop 1
	v_mov_b32_dpp v71, v67 quad_perm:[2,3,0,1] row_mask:0xf bank_mask:0xf
	v_mov_b32_e32 v141, v1
	v_lshl_add_u64 v[140:141], v[110:111], 0, v[140:141]
	global_store_dwordx2 v[140:141], v[134:135], off
	s_waitcnt lgkmcnt(0)
	v_add_f32_e32 v67, v67, v71
	s_nop 1
	v_mov_b32_dpp v71, v67 row_half_mirror row_mask:0xf bank_mask:0xf
	s_waitcnt lgkmcnt(0)
	v_add_f32_e32 v67, v67, v71
	s_nop 1
	v_mov_b32_dpp v71, v67 row_mirror row_mask:0xf bank_mask:0xf
	v_add_f32_e32 v146, v67, v71
	v_cmp_eq_u32_e64 s[4:5], 3, v180
	s_nop 1
	v_cndmask_b32_e64 v147, v147, v146, s[4:5]
; DI float bflo(unsigned v) { return __uint_as_float(v << 16); }
; DI float bfhi(unsigned v) { return __uint_as_float(v & 0xffff0000u); }
; template <int EPI>
; DI void gemm_tile(const Params& p, int layer, int mt, int nt, u16* sm, int wv) {
;     ...
;       for (int t = 0; t < 16; ++t) {
;         const int row = (lane >> 4) + 4 * t;
;         const f32x4 a4 = *(const f32x4*)(stg + row * 68 + kc * 4);
;         const float v0 = bflo(xb[t][0]) + a4[0], v1 = bfhi(xb[t][0]) + a4[1], v2 = bflo(xb[t][1]) + a4[2], v3 = bfhi(xb[t][1]) + a4[3];
;         float sq = v0 * v0 + v1 * v1 + v2 * v2 + v3 * v3;
;         u32x2 pv = {pk2(v0, v1), pk2(v2, v3)};
;         if (has_next) *(u32x2*)(xrow + (size_t)row * DM) = pv;
;         else *(u32x2*)(x2row + (size_t)row * DM) = pv;
;         sq += shx(sq, lane, 1); sq += shx(sq, lane, 2); sq += shx(sq, lane, 4); sq += shx(sq, lane, 8);
;         if (kc == 0) atomicAdd(ssn + mrow0 + row, sq);
.LBB0_411:
	ds_read_b128 v[140:143], v69 offset:4352
	v_lshlrev_b32_e32 v134, 16, v126
	v_and_b32_e32 v135, 0xffff0000, v126
	v_lshlrev_b32_e32 v126, 16, v127
	v_and_b32_e32 v127, 0xffff0000, v127
	s_waitcnt lgkmcnt(0)
	v_pk_add_f32 v[134:135], v[140:141], v[134:135]
	v_pk_add_f32 v[140:141], v[142:143], v[126:127]
	v_pk_mul_f32 v[126:127], v[134:135], v[134:135]
	v_pk_mul_f32 v[142:143], v[140:141], v[140:141]
	v_add_f32_e32 v67, v126, v127
	v_add_f32_e32 v67, v142, v67
	v_add_f32_e32 v67, v143, v67
	s_nop 1
	v_mov_b32_dpp v71, v67 quad_perm:[1,0,3,2] row_mask:0xf bank_mask:0xf
	v_or_b32_e32 v126, 16, v183
	v_cvt_pk_bf16_f32 v134, v134, v135
	v_cvt_pk_bf16_f32 v135, v140, v141
	v_lshlrev_b32_e32 v140, 11, v126
	s_waitcnt lgkmcnt(0)
	v_add_f32_e32 v67, v67, v71
	s_nop 1
	v_mov_b32_dpp v71, v67 quad_perm:[2,3,0,1] row_mask:0xf bank_mask:0xf
	v_mov_b32_e32 v141, v1
	v_lshl_add_u64 v[140:141], v[110:111], 0, v[140:141]
	global_store_dwordx2 v[140:141], v[134:135], off
	s_waitcnt lgkmcnt(0)
	v_add_f32_e32 v67, v67, v71
	s_nop 1
	v_mov_b32_dpp v71, v67 row_half_mirror row_mask:0xf bank_mask:0xf
	s_waitcnt lgkmcnt(0)
	v_add_f32_e32 v67, v67, v71
	s_nop 1
	v_mov_b32_dpp v71, v67 row_mirror row_mask:0xf bank_mask:0xf
	v_add_f32_e32 v146, v67, v71
	v_cmp_eq_u32_e64 s[4:5], 4, v180
	s_nop 1
	v_cndmask_b32_e64 v147, v147, v146, s[4:5]
.LBB0_413:
	ds_read_b128 v[140:143], v69 offset:5440
	v_lshlrev_b32_e32 v134, 16, v124
	v_and_b32_e32 v135, 0xffff0000, v124
	v_lshlrev_b32_e32 v124, 16, v125
	v_and_b32_e32 v125, 0xffff0000, v125
	s_waitcnt lgkmcnt(0)
	v_pk_add_f32 v[134:135], v[140:141], v[134:135]
	v_pk_add_f32 v[140:141], v[142:143], v[124:125]
	v_pk_mul_f32 v[124:125], v[134:135], v[134:135]
	v_pk_mul_f32 v[142:143], v[140:141], v[140:141]
	v_add_f32_e32 v67, v124, v125
	v_add_f32_e32 v67, v142, v67
	v_add_f32_e32 v67, v143, v67
	s_nop 1
	v_mov_b32_dpp v71, v67 quad_perm:[1,0,3,2] row_mask:0xf bank_mask:0xf
	v_or_b32_e32 v124, 20, v183
	v_cvt_pk_bf16_f32 v134, v134, v135
	v_cvt_pk_bf16_f32 v135, v140, v141
	v_lshlrev_b32_e32 v140, 11, v124
	s_waitcnt lgkmcnt(0)
	v_add_f32_e32 v67, v67, v71
	s_nop 1
	v_mov_b32_dpp v71, v67 quad_perm:[2,3,0,1] row_mask:0xf bank_mask:0xf
	v_mov_b32_e32 v141, v1
	v_lshl_add_u64 v[140:141], v[110:111], 0, v[140:141]
	global_store_dwordx2 v[140:141], v[134:135], off
	s_waitcnt lgkmcnt(0)
	v_add_f32_e32 v67, v67, v71
	s_nop 1
	v_mov_b32_dpp v71, v67 row_half_mirror row_mask:0xf bank_mask:0xf
	s_waitcnt lgkmcnt(0)
	v_add_f32_e32 v67, v67, v71
	s_nop 1
	v_mov_b32_dpp v71, v67 row_mirror row_mask:0xf bank_mask:0xf
	v_add_f32_e32 v146, v67, v71
	v_cmp_eq_u32_e64 s[4:5], 5, v180
	s_nop 1
	v_cndmask_b32_e64 v147, v147, v146, s[4:5]
.LBB0_415:
	ds_read_b128 v[140:143], v69 offset:6528
	v_lshlrev_b32_e32 v134, 16, v122
	v_and_b32_e32 v135, 0xffff0000, v122
	v_lshlrev_b32_e32 v122, 16, v123
	v_and_b32_e32 v123, 0xffff0000, v123
	s_waitcnt lgkmcnt(0)
	v_pk_add_f32 v[134:135], v[140:141], v[134:135]
	v_pk_add_f32 v[140:141], v[142:143], v[122:123]
	v_pk_mul_f32 v[122:123], v[134:135], v[134:135]
	v_pk_mul_f32 v[142:143], v[140:141], v[140:141]
	v_add_f32_e32 v67, v122, v123
	v_add_f32_e32 v67, v142, v67
	v_add_f32_e32 v67, v143, v67
	s_nop 1
	v_mov_b32_dpp v71, v67 quad_perm:[1,0,3,2] row_mask:0xf bank_mask:0xf
	v_or_b32_e32 v122, 24, v183
	v_cvt_pk_bf16_f32 v134, v134, v135
	v_cvt_pk_bf16_f32 v135, v140, v141
	v_lshlrev_b32_e32 v140, 11, v122
	s_waitcnt lgkmcnt(0)
	v_add_f32_e32 v67, v67, v71
	s_nop 1
	v_mov_b32_dpp v71, v67 quad_perm:[2,3,0,1] row_mask:0xf bank_mask:0xf
	v_mov_b32_e32 v141, v1
	v_lshl_add_u64 v[140:141], v[110:111], 0, v[140:141]
	global_store_dwordx2 v[140:141], v[134:135], off
	s_waitcnt lgkmcnt(0)
	v_add_f32_e32 v67, v67, v71
	s_nop 1
	v_mov_b32_dpp v71, v67 row_half_mirror row_mask:0xf bank_mask:0xf
	s_waitcnt lgkmcnt(0)
	v_add_f32_e32 v67, v67, v71
	s_nop 1
	v_mov_b32_dpp v71, v67 row_mirror row_mask:0xf bank_mask:0xf
	v_add_f32_e32 v146, v67, v71
	v_cmp_eq_u32_e64 s[4:5], 6, v180
	s_nop 1
	v_cndmask_b32_e64 v147, v147, v146, s[4:5]
.LBB0_417:
	ds_read_b128 v[140:143], v69 offset:7616
	v_lshlrev_b32_e32 v134, 16, v120
	v_and_b32_e32 v135, 0xffff0000, v120
	v_lshlrev_b32_e32 v120, 16, v121
	v_and_b32_e32 v121, 0xffff0000, v121
	s_waitcnt lgkmcnt(0)
	v_pk_add_f32 v[134:135], v[140:141], v[134:135]
	v_pk_add_f32 v[140:141], v[142:143], v[120:121]
	v_pk_mul_f32 v[120:121], v[134:135], v[134:135]
	v_pk_mul_f32 v[142:143], v[140:141], v[140:141]
	v_add_f32_e32 v67, v120, v121
	v_add_f32_e32 v67, v142, v67
	v_add_f32_e32 v67, v143, v67
	s_nop 1
	v_mov_b32_dpp v71, v67 quad_perm:[1,0,3,2] row_mask:0xf bank_mask:0xf
	v_or_b32_e32 v120, 28, v183
	v_cvt_pk_bf16_f32 v134, v134, v135
	v_cvt_pk_bf16_f32 v135, v140, v141
	v_lshlrev_b32_e32 v140, 11, v120
	s_waitcnt lgkmcnt(0)
	v_add_f32_e32 v67, v67, v71
	s_nop 1
	v_mov_b32_dpp v71, v67 quad_perm:[2,3,0,1] row_mask:0xf bank_mask:0xf
	v_mov_b32_e32 v141, v1
	v_lshl_add_u64 v[140:141], v[110:111], 0, v[140:141]
	global_store_dwordx2 v[140:141], v[134:135], off
	s_waitcnt lgkmcnt(0)
	v_add_f32_e32 v67, v67, v71
	s_nop 1
	v_mov_b32_dpp v71, v67 row_half_mirror row_mask:0xf bank_mask:0xf
	s_waitcnt lgkmcnt(0)
	v_add_f32_e32 v67, v67, v71
	s_nop 1
	v_mov_b32_dpp v71, v67 row_mirror row_mask:0xf bank_mask:0xf
	v_add_f32_e32 v146, v67, v71
	v_cmp_eq_u32_e64 s[4:5], 7, v180
	s_nop 1
	v_cndmask_b32_e64 v147, v147, v146, s[4:5]
; DI float bflo(unsigned v) { return __uint_as_float(v << 16); }
; DI float bfhi(unsigned v) { return __uint_as_float(v & 0xffff0000u); }
; template <int EPI>
; DI void gemm_tile(const Params& p, int layer, int mt, int nt, u16* sm, int wv) {
;     ...
;       for (int t = 0; t < 16; ++t) {
;         const int row = (lane >> 4) + 4 * t;
;         const f32x4 a4 = *(const f32x4*)(stg + row * 68 + kc * 4);
;         const float v0 = bflo(xb[t][0]) + a4[0], v1 = bfhi(xb[t][0]) + a4[1], v2 = bflo(xb[t][1]) + a4[2], v3 = bfhi(xb[t][1]) + a4[3];
;         float sq = v0 * v0 + v1 * v1 + v2 * v2 + v3 * v3;
;         u32x2 pv = {pk2(v0, v1), pk2(v2, v3)};
;         if (has_next) *(u32x2*)(xrow + (size_t)row * DM) = pv;
;         else *(u32x2*)(x2row + (size_t)row * DM) = pv;
;         sq += shx(sq, lane, 1); sq += shx(sq, lane, 2); sq += shx(sq, lane, 4); sq += shx(sq, lane, 8);
;         if (kc == 0) atomicAdd(ssn + mrow0 + row, sq);
.LBB0_419:
	ds_read_b128 v[140:143], v69 offset:8704
	v_lshlrev_b32_e32 v134, 16, v118
	v_and_b32_e32 v135, 0xffff0000, v118
	v_lshlrev_b32_e32 v118, 16, v119
	v_and_b32_e32 v119, 0xffff0000, v119
	s_waitcnt lgkmcnt(0)
	v_pk_add_f32 v[134:135], v[140:141], v[134:135]
	v_pk_add_f32 v[140:141], v[142:143], v[118:119]
	v_pk_mul_f32 v[118:119], v[134:135], v[134:135]
	v_pk_mul_f32 v[142:143], v[140:141], v[140:141]
	v_add_f32_e32 v67, v118, v119
	v_add_f32_e32 v67, v142, v67
	v_add_f32_e32 v67, v143, v67
	s_nop 1
	v_mov_b32_dpp v71, v67 quad_perm:[1,0,3,2] row_mask:0xf bank_mask:0xf
	v_or_b32_e32 v118, 32, v183
	v_cvt_pk_bf16_f32 v134, v134, v135
	v_cvt_pk_bf16_f32 v135, v140, v141
	v_lshlrev_b32_e32 v140, 11, v118
	s_waitcnt lgkmcnt(0)
	v_add_f32_e32 v67, v67, v71
	s_nop 1
	v_mov_b32_dpp v71, v67 quad_perm:[2,3,0,1] row_mask:0xf bank_mask:0xf
	v_mov_b32_e32 v141, v1
	v_lshl_add_u64 v[140:141], v[110:111], 0, v[140:141]
	global_store_dwordx2 v[140:141], v[134:135], off
	s_waitcnt lgkmcnt(0)
	v_add_f32_e32 v67, v67, v71
	s_nop 1
	v_mov_b32_dpp v71, v67 row_half_mirror row_mask:0xf bank_mask:0xf
	s_waitcnt lgkmcnt(0)
	v_add_f32_e32 v67, v67, v71
	s_nop 1
	v_mov_b32_dpp v71, v67 row_mirror row_mask:0xf bank_mask:0xf
	v_add_f32_e32 v146, v67, v71
	v_cmp_eq_u32_e64 s[4:5], 8, v180
	s_nop 1
	v_cndmask_b32_e64 v147, v147, v146, s[4:5]
.LBB0_421:
	ds_read_b128 v[140:143], v69 offset:9792
	v_lshlrev_b32_e32 v134, 16, v116
	v_and_b32_e32 v135, 0xffff0000, v116
	v_lshlrev_b32_e32 v116, 16, v117
	v_and_b32_e32 v117, 0xffff0000, v117
	s_waitcnt lgkmcnt(0)
	v_pk_add_f32 v[134:135], v[140:141], v[134:135]
	v_pk_add_f32 v[140:141], v[142:143], v[116:117]
	v_pk_mul_f32 v[116:117], v[134:135], v[134:135]
	v_pk_mul_f32 v[142:143], v[140:141], v[140:141]
	v_add_f32_e32 v67, v116, v117
	v_add_f32_e32 v67, v142, v67
	v_add_f32_e32 v67, v143, v67
	s_nop 1
	v_mov_b32_dpp v71, v67 quad_perm:[1,0,3,2] row_mask:0xf bank_mask:0xf
	v_or_b32_e32 v116, 36, v183
	v_cvt_pk_bf16_f32 v134, v134, v135
	v_cvt_pk_bf16_f32 v135, v140, v141
	v_lshlrev_b32_e32 v140, 11, v116
	s_waitcnt lgkmcnt(0)
	v_add_f32_e32 v67, v67, v71
	s_nop 1
	v_mov_b32_dpp v71, v67 quad_perm:[2,3,0,1] row_mask:0xf bank_mask:0xf
	v_mov_b32_e32 v141, v1
	v_lshl_add_u64 v[140:141], v[110:111], 0, v[140:141]
	global_store_dwordx2 v[140:141], v[134:135], off
	s_waitcnt lgkmcnt(0)
	v_add_f32_e32 v67, v67, v71
	s_nop 1
	v_mov_b32_dpp v71, v67 row_half_mirror row_mask:0xf bank_mask:0xf
	s_waitcnt lgkmcnt(0)
	v_add_f32_e32 v67, v67, v71
	s_nop 1
	v_mov_b32_dpp v71, v67 row_mirror row_mask:0xf bank_mask:0xf
	v_add_f32_e32 v146, v67, v71
	v_cmp_eq_u32_e64 s[4:5], 9, v180
	s_nop 1
	v_cndmask_b32_e64 v147, v147, v146, s[4:5]
.LBB0_423:
	ds_read_b128 v[140:143], v69 offset:10880
	v_lshlrev_b32_e32 v134, 16, v114
	v_and_b32_e32 v135, 0xffff0000, v114
	v_lshlrev_b32_e32 v114, 16, v115
	v_and_b32_e32 v115, 0xffff0000, v115
	s_waitcnt lgkmcnt(0)
	v_pk_add_f32 v[134:135], v[140:141], v[134:135]
	v_pk_add_f32 v[140:141], v[142:143], v[114:115]
	v_pk_mul_f32 v[114:115], v[134:135], v[134:135]
	v_pk_mul_f32 v[142:143], v[140:141], v[140:141]
	v_add_f32_e32 v67, v114, v115
	v_add_f32_e32 v67, v142, v67
	v_add_f32_e32 v67, v143, v67
	s_nop 1
	v_mov_b32_dpp v71, v67 quad_perm:[1,0,3,2] row_mask:0xf bank_mask:0xf
	v_or_b32_e32 v114, 40, v183
	v_cvt_pk_bf16_f32 v134, v134, v135
	v_cvt_pk_bf16_f32 v135, v140, v141
	v_lshlrev_b32_e32 v140, 11, v114
	s_waitcnt lgkmcnt(0)
	v_add_f32_e32 v67, v67, v71
	s_nop 1
	v_mov_b32_dpp v71, v67 quad_perm:[2,3,0,1] row_mask:0xf bank_mask:0xf
	v_mov_b32_e32 v141, v1
	v_lshl_add_u64 v[140:141], v[110:111], 0, v[140:141]
	global_store_dwordx2 v[140:141], v[134:135], off
	s_waitcnt lgkmcnt(0)
	v_add_f32_e32 v67, v67, v71
	s_nop 1
	v_mov_b32_dpp v71, v67 row_half_mirror row_mask:0xf bank_mask:0xf
	s_waitcnt lgkmcnt(0)
	v_add_f32_e32 v67, v67, v71
	s_nop 1
	v_mov_b32_dpp v71, v67 row_mirror row_mask:0xf bank_mask:0xf
	v_add_f32_e32 v146, v67, v71
	v_cmp_eq_u32_e64 s[4:5], 10, v180
	s_nop 1
	v_cndmask_b32_e64 v147, v147, v146, s[4:5]
.LBB0_425:
	ds_read_b128 v[140:143], v69 offset:11968
	v_lshlrev_b32_e32 v134, 16, v112
	v_and_b32_e32 v135, 0xffff0000, v112
	v_lshlrev_b32_e32 v112, 16, v113
	v_and_b32_e32 v113, 0xffff0000, v113
	s_waitcnt lgkmcnt(0)
	v_pk_add_f32 v[134:135], v[140:141], v[134:135]
	v_pk_add_f32 v[140:141], v[142:143], v[112:113]
	v_pk_mul_f32 v[112:113], v[134:135], v[134:135]
	v_pk_mul_f32 v[142:143], v[140:141], v[140:141]
	v_add_f32_e32 v67, v112, v113
	v_add_f32_e32 v67, v142, v67
	v_add_f32_e32 v67, v143, v67
	s_nop 1
	v_mov_b32_dpp v71, v67 quad_perm:[1,0,3,2] row_mask:0xf bank_mask:0xf
	v_or_b32_e32 v112, 44, v183
	v_cvt_pk_bf16_f32 v134, v134, v135
	v_cvt_pk_bf16_f32 v135, v140, v141
	v_lshlrev_b32_e32 v140, 11, v112
	s_waitcnt lgkmcnt(0)
	v_add_f32_e32 v67, v67, v71
	s_nop 1
	v_mov_b32_dpp v71, v67 quad_perm:[2,3,0,1] row_mask:0xf bank_mask:0xf
	v_mov_b32_e32 v141, v1
	v_lshl_add_u64 v[140:141], v[110:111], 0, v[140:141]
	global_store_dwordx2 v[140:141], v[134:135], off
	s_waitcnt lgkmcnt(0)
	v_add_f32_e32 v67, v67, v71
	s_nop 1
	v_mov_b32_dpp v71, v67 row_half_mirror row_mask:0xf bank_mask:0xf
	s_waitcnt lgkmcnt(0)
	v_add_f32_e32 v67, v67, v71
	s_nop 1
	v_mov_b32_dpp v71, v67 row_mirror row_mask:0xf bank_mask:0xf
	v_add_f32_e32 v146, v67, v71
	v_cmp_eq_u32_e64 s[4:5], 11, v180
	s_nop 1
	v_cndmask_b32_e64 v147, v147, v146, s[4:5]
; DI float bflo(unsigned v) { return __uint_as_float(v << 16); }
; DI float bfhi(unsigned v) { return __uint_as_float(v & 0xffff0000u); }
; template <int EPI>
; DI void gemm_tile(const Params& p, int layer, int mt, int nt, u16* sm, int wv) {
;     ...
;       for (int t = 0; t < 16; ++t) {
;         const int row = (lane >> 4) + 4 * t;
;         const f32x4 a4 = *(const f32x4*)(stg + row * 68 + kc * 4);
;         const float v0 = bflo(xb[t][0]) + a4[0], v1 = bfhi(xb[t][0]) + a4[1], v2 = bflo(xb[t][1]) + a4[2], v3 = bfhi(xb[t][1]) + a4[3];
;         float sq = v0 * v0 + v1 * v1 + v2 * v2 + v3 * v3;
;         u32x2 pv = {pk2(v0, v1), pk2(v2, v3)};
;         if (has_next) *(u32x2*)(xrow + (size_t)row * DM) = pv;
;         else *(u32x2*)(x2row + (size_t)row * DM) = pv;
;         sq += shx(sq, lane, 1); sq += shx(sq, lane, 2); sq += shx(sq, lane, 4); sq += shx(sq, lane, 8);
;         if (kc == 0) atomicAdd(ssn + mrow0 + row, sq);
.LBB0_427:
	ds_read_b128 v[140:143], v69 offset:13056
	v_lshlrev_b32_e32 v134, 16, v108
	v_and_b32_e32 v135, 0xffff0000, v108
	v_lshlrev_b32_e32 v108, 16, v109
	v_and_b32_e32 v109, 0xffff0000, v109
	s_waitcnt lgkmcnt(0)
	v_pk_add_f32 v[134:135], v[140:141], v[134:135]
	v_pk_add_f32 v[140:141], v[142:143], v[108:109]
	v_pk_mul_f32 v[108:109], v[134:135], v[134:135]
	v_pk_mul_f32 v[142:143], v[140:141], v[140:141]
	v_add_f32_e32 v67, v108, v109
	v_add_f32_e32 v67, v142, v67
	v_add_f32_e32 v67, v143, v67
	s_nop 1
	v_mov_b32_dpp v71, v67 quad_perm:[1,0,3,2] row_mask:0xf bank_mask:0xf
	v_or_b32_e32 v108, 48, v183
	v_cvt_pk_bf16_f32 v134, v134, v135
	v_cvt_pk_bf16_f32 v135, v140, v141
	v_lshlrev_b32_e32 v140, 11, v108
	s_waitcnt lgkmcnt(0)
	v_add_f32_e32 v67, v67, v71
	s_nop 1
	v_mov_b32_dpp v71, v67 quad_perm:[2,3,0,1] row_mask:0xf bank_mask:0xf
	v_mov_b32_e32 v141, v1
	v_lshl_add_u64 v[140:141], v[110:111], 0, v[140:141]
	global_store_dwordx2 v[140:141], v[134:135], off
	s_waitcnt lgkmcnt(0)
	v_add_f32_e32 v67, v67, v71
	s_nop 1
	v_mov_b32_dpp v71, v67 row_half_mirror row_mask:0xf bank_mask:0xf
	s_waitcnt lgkmcnt(0)
	v_add_f32_e32 v67, v67, v71
	s_nop 1
	v_mov_b32_dpp v71, v67 row_mirror row_mask:0xf bank_mask:0xf
	v_add_f32_e32 v146, v67, v71
	v_cmp_eq_u32_e64 s[4:5], 12, v180
	s_nop 1
	v_cndmask_b32_e64 v147, v147, v146, s[4:5]
.LBB0_429:
	ds_read_b128 v[140:143], v69 offset:14144
	s_waitcnt vmcnt(14)
	v_lshlrev_b32_e32 v134, 16, v106
	v_and_b32_e32 v135, 0xffff0000, v106
	v_lshlrev_b32_e32 v106, 16, v107
	v_and_b32_e32 v107, 0xffff0000, v107
	s_waitcnt lgkmcnt(0)
	v_pk_add_f32 v[134:135], v[140:141], v[134:135]
	v_pk_add_f32 v[140:141], v[142:143], v[106:107]
	v_pk_mul_f32 v[106:107], v[134:135], v[134:135]
	v_pk_mul_f32 v[142:143], v[140:141], v[140:141]
	v_add_f32_e32 v67, v106, v107
	v_add_f32_e32 v67, v142, v67
	v_add_f32_e32 v67, v143, v67
	s_nop 1
	v_mov_b32_dpp v71, v67 quad_perm:[1,0,3,2] row_mask:0xf bank_mask:0xf
	v_or_b32_e32 v106, 52, v183
	v_cvt_pk_bf16_f32 v134, v134, v135
	v_cvt_pk_bf16_f32 v135, v140, v141
	v_lshlrev_b32_e32 v140, 11, v106
	s_waitcnt lgkmcnt(0)
	v_add_f32_e32 v67, v67, v71
	s_nop 1
	v_mov_b32_dpp v71, v67 quad_perm:[2,3,0,1] row_mask:0xf bank_mask:0xf
	v_mov_b32_e32 v141, v1
	v_lshl_add_u64 v[140:141], v[110:111], 0, v[140:141]
	global_store_dwordx2 v[140:141], v[134:135], off
	s_waitcnt lgkmcnt(0)
	v_add_f32_e32 v67, v67, v71
	s_nop 1
	v_mov_b32_dpp v71, v67 row_half_mirror row_mask:0xf bank_mask:0xf
	s_waitcnt lgkmcnt(0)
	v_add_f32_e32 v67, v67, v71
	s_nop 1
	v_mov_b32_dpp v71, v67 row_mirror row_mask:0xf bank_mask:0xf
	v_add_f32_e32 v146, v67, v71
	v_cmp_eq_u32_e64 s[4:5], 13, v180
	s_nop 1
	v_cndmask_b32_e64 v147, v147, v146, s[4:5]
.LBB0_431:
	ds_read_b128 v[140:143], v69 offset:15232
	s_waitcnt vmcnt(14)
	v_lshlrev_b32_e32 v134, 16, v102
	v_and_b32_e32 v135, 0xffff0000, v102
	v_lshlrev_b32_e32 v102, 16, v103
	v_and_b32_e32 v103, 0xffff0000, v103
	s_waitcnt lgkmcnt(0)
	v_pk_add_f32 v[134:135], v[140:141], v[134:135]
	v_pk_add_f32 v[140:141], v[142:143], v[102:103]
	v_pk_mul_f32 v[102:103], v[134:135], v[134:135]
	v_pk_mul_f32 v[142:143], v[140:141], v[140:141]
	v_add_f32_e32 v67, v102, v103
	v_add_f32_e32 v67, v142, v67
	v_add_f32_e32 v67, v143, v67
	s_nop 1
	v_mov_b32_dpp v71, v67 quad_perm:[1,0,3,2] row_mask:0xf bank_mask:0xf
	v_or_b32_e32 v103, 56, v183
	v_cvt_pk_bf16_f32 v134, v134, v135
	v_cvt_pk_bf16_f32 v135, v140, v141
	v_lshlrev_b32_e32 v140, 11, v103
	s_waitcnt lgkmcnt(0)
	v_add_f32_e32 v67, v67, v71
	s_nop 1
	v_mov_b32_dpp v71, v67 quad_perm:[2,3,0,1] row_mask:0xf bank_mask:0xf
	v_mov_b32_e32 v141, v1
	v_lshl_add_u64 v[140:141], v[110:111], 0, v[140:141]
	global_store_dwordx2 v[140:141], v[134:135], off
	s_waitcnt lgkmcnt(0)
	v_add_f32_e32 v67, v67, v71
	s_nop 1
	v_mov_b32_dpp v71, v67 row_half_mirror row_mask:0xf bank_mask:0xf
	s_waitcnt lgkmcnt(0)
	v_add_f32_e32 v67, v67, v71
	s_nop 1
	v_mov_b32_dpp v71, v67 row_mirror row_mask:0xf bank_mask:0xf
	v_add_f32_e32 v146, v67, v71
	v_cmp_eq_u32_e64 s[4:5], 14, v180
	s_nop 1
	v_cndmask_b32_e64 v147, v147, v146, s[4:5]
; DI float bflo(unsigned v) { return __uint_as_float(v << 16); }
; DI float bfhi(unsigned v) { return __uint_as_float(v & 0xffff0000u); }
; template <int EPI>
; DI void gemm_tile(const Params& p, int layer, int mt, int nt, u16* sm, int wv) {
;     ...
; #pragma unroll
;       for (int i2 = 0; i2 < 4; ++i2)
; #pragma unroll
;         for (int j = 0; j < 4; ++j)
;           *(f32x4*)(stg + (16 * i2 + fr) * 68 + 16 * j + 4 * fq) = acc[4 * hh + i2][j];
;       const size_t mrow0 = (size_t)(m0 + wm * 128 + 64 * hh);
;       u16* xrow = p.xg + mrow0 * DM + n0 + wn * 64 + kc * 4;
;       u16* x2row = (u16*)p.x2 + mrow0 * DM + n0 + wn * 64 + kc * 4;
;       u32x2 xb[16];
; #pragma unroll
;       for (int t = 0; t < 16; ++t) xb[t] = __builtin_nontemporal_load((const u32x2*)(xrow + (size_t)((lane >> 4) + 4 * t) * DM));
; #pragma unroll
;       for (int t = 0; t < 16; ++t) {
;         const int row = (lane >> 4) + 4 * t;
;         const f32x4 a4 = *(const f32x4*)(stg + row * 68 + kc * 4);
;         const float v0 = bflo(xb[t][0]) + a4[0], v1 = bfhi(xb[t][0]) + a4[1], v2 = bflo(xb[t][1]) + a4[2], v3 = bfhi(xb[t][1]) + a4[3];
;         float sq = v0 * v0 + v1 * v1 + v2 * v2 + v3 * v3;
;         u32x2 pv = {pk2(v0, v1), pk2(v2, v3)};
;         if (has_next) *(u32x2*)(xrow + (size_t)row * DM) = pv;
;         else *(u32x2*)(x2row + (size_t)row * DM) = pv;
;         sq += shx(sq, lane, 1); sq += shx(sq, lane, 2); sq += shx(sq, lane, 4); sq += shx(sq, lane, 8);
;         if (kc == 0) atomicAdd(ssn + mrow0 + row, sq);
.LBB0_433:
	ds_read_b128 v[140:143], v69 offset:16320
	s_waitcnt vmcnt(14)
	v_lshlrev_b32_e32 v134, 16, v100
	v_and_b32_e32 v135, 0xffff0000, v100
	v_lshlrev_b32_e32 v100, 16, v101
	v_and_b32_e32 v101, 0xffff0000, v101
	s_waitcnt lgkmcnt(0)
	v_pk_add_f32 v[134:135], v[140:141], v[134:135]
	v_pk_add_f32 v[100:101], v[142:143], v[100:101]
	v_pk_mul_f32 v[140:141], v[134:135], v[134:135]
	v_pk_mul_f32 v[142:143], v[100:101], v[100:101]
	v_add_f32_e32 v67, v140, v141
	v_add_f32_e32 v67, v142, v67
	v_add_f32_e32 v67, v143, v67
	s_nop 1
	v_mov_b32_dpp v71, v67 quad_perm:[1,0,3,2] row_mask:0xf bank_mask:0xf
	v_or_b32_e32 v102, 60, v183
	v_cvt_pk_bf16_f32 v134, v134, v135
	v_cvt_pk_bf16_f32 v135, v100, v101
	v_lshlrev_b32_e32 v100, 11, v102
	s_waitcnt lgkmcnt(0)
	v_add_f32_e32 v67, v67, v71
	s_nop 1
	v_mov_b32_dpp v71, v67 quad_perm:[2,3,0,1] row_mask:0xf bank_mask:0xf
	v_mov_b32_e32 v101, v1
	v_lshl_add_u64 v[100:101], v[110:111], 0, v[100:101]
	global_store_dwordx2 v[100:101], v[134:135], off
	s_waitcnt lgkmcnt(0)
	v_add_f32_e32 v67, v67, v71
	s_nop 1
	v_mov_b32_dpp v71, v67 row_half_mirror row_mask:0xf bank_mask:0xf
	s_waitcnt lgkmcnt(0)
	v_add_f32_e32 v67, v67, v71
	s_nop 1
	v_mov_b32_dpp v71, v67 row_mirror row_mask:0xf bank_mask:0xf
	v_add_f32_e32 v146, v67, v71
	v_cmp_eq_u32_e64 s[4:5], 15, v180
	s_nop 1
	v_cndmask_b32_e64 v147, v147, v146, s[4:5]
.LBB0_435:
	v_lshl_add_u32 v148, v180, 4, v66
	v_mov_b32_e32 v149, v1
	v_lshl_add_u64 v[148:149], v[104:105], 0, v[148:149]
	global_atomic_add_f32 v[148:149], v147, off
	v_mul_u32_u24_e32 v73, 0x110, v180
	v_add_u32_e32 v73, v182, v73
	ds_write_b128 v73, v[62:65]
	ds_write_b128 v73, v[58:61] offset:64
	ds_write_b128 v73, v[54:57] offset:128
	ds_write_b128 v73, v[50:53] offset:192
	ds_write_b128 v73, v[46:49] offset:4352
	ds_write_b128 v73, v[42:45] offset:4416
	ds_write_b128 v73, v[38:41] offset:4480
	ds_write_b128 v73, v[34:37] offset:4544
	ds_write_b128 v73, v[30:33] offset:8704
	ds_write_b128 v73, v[26:29] offset:8768
	ds_write_b128 v73, v[22:25] offset:8832
	ds_write_b128 v73, v[18:21] offset:8896
	ds_write_b128 v73, v[10:13] offset:13056
	ds_write_b128 v73, v[6:9] offset:13120
	ds_write_b128 v73, v[2:5] offset:13184
	ds_write_b128 v73, v[14:17] offset:13248
	v_or_b32_e32 v4, 64, v68
	v_ashrrev_i32_e32 v5, 31, v4
	v_lshlrev_b64 v[2:3], 11, v[4:5]
	v_lshlrev_b32_e32 v67, 6, v181
	v_lshl_add_u64 v[6:7], s[60:61], 0, v[2:3]
	s_waitcnt lgkmcnt(14)
	v_lshlrev_b32_e32 v71, 2, v180
	v_lshl_add_u64 v[6:7], v[6:7], 0, s[2:3]
	v_lshlrev_b32_e32 v8, 1, v67
	v_mov_b32_e32 v9, v1
	v_lshl_add_u64 v[6:7], v[6:7], 0, v[8:9]
	v_lshlrev_b32_e32 v38, 1, v71
	v_mov_b32_e32 v39, v1
	v_lshl_add_u64 v[2:3], s[82:83], 0, v[2:3]
	v_lshl_add_u64 v[10:11], v[6:7], 0, v[38:39]
	v_lshl_add_u64 v[2:3], v[2:3], 0, s[2:3]
	v_mov_b32_e32 v71, v1
	v_lshl_add_u64 v[40:41], v[2:3], 0, v[8:9]
	v_lshl_add_u64 v[2:3], v[10:11], 0, v[70:71]
	v_mov_b32_e32 v73, v1
	global_load_dwordx2 v[34:35], v[2:3], off nt
	v_lshl_add_u64 v[2:3], v[10:11], 0, v[72:73]
	v_mov_b32_e32 v75, v1
	global_load_dwordx2 v[32:33], v[2:3], off nt
	v_lshl_add_u64 v[2:3], v[10:11], 0, v[74:75]
	v_mov_b32_e32 v81, v1
	global_load_dwordx2 v[30:31], v[2:3], off nt
	v_lshl_add_u64 v[2:3], v[10:11], 0, v[80:81]
	v_mov_b32_e32 v77, v1
	global_load_dwordx2 v[28:29], v[2:3], off nt
	v_lshl_add_u64 v[2:3], v[10:11], 0, v[76:77]
	v_mov_b32_e32 v79, v1
	global_load_dwordx2 v[26:27], v[2:3], off nt
	v_lshl_add_u64 v[2:3], v[10:11], 0, v[78:79]
	v_mov_b32_e32 v83, v1
	global_load_dwordx2 v[24:25], v[2:3], off nt
	v_lshl_add_u64 v[2:3], v[10:11], 0, v[82:83]
	v_mov_b32_e32 v89, v1
	global_load_dwordx2 v[22:23], v[2:3], off nt
	v_lshl_add_u64 v[2:3], v[10:11], 0, v[88:89]
	v_mov_b32_e32 v85, v1
	global_load_dwordx2 v[20:21], v[2:3], off nt
	v_lshl_add_u64 v[2:3], v[10:11], 0, v[84:85]
	v_mov_b32_e32 v87, v1
	global_load_dwordx2 v[18:19], v[2:3], off nt
	v_lshl_add_u64 v[2:3], v[10:11], 0, v[86:87]
	v_mov_b32_e32 v91, v1
	global_load_dwordx2 v[16:17], v[2:3], off nt
	v_lshl_add_u64 v[2:3], v[10:11], 0, v[90:91]
	v_mov_b32_e32 v97, v1
	v_lshl_add_u64 v[36:37], v[10:11], 0, v[0:1]
	global_load_dwordx2 v[14:15], v[2:3], off nt
	v_lshl_add_u64 v[2:3], v[10:11], 0, v[96:97]
	v_mov_b32_e32 v93, v1
	global_load_dwordx2 v[44:45], v[36:37], off nt
	global_load_dwordx2 v[12:13], v[2:3], off nt
	v_lshl_add_u64 v[2:3], v[10:11], 0, v[92:93]
	v_mov_b32_e32 v95, v1
	global_load_dwordx2 v[8:9], v[2:3], off nt
	v_lshl_add_u64 v[2:3], v[10:11], 0, v[94:95]
	v_mov_b32_e32 v99, v1
	global_load_dwordx2 v[6:7], v[2:3], off nt
	v_lshl_add_u64 v[2:3], v[10:11], 0, v[98:99]
	global_load_dwordx2 v[2:3], v[2:3], off nt
	v_lshl_add_u64 v[38:39], v[40:41], 0, v[38:39]
	ds_read_b128 v[40:43], v69
	s_mov_b64 s[2:3], -1
	s_andn2_b64 vcc, exec, s[70:71]
	s_waitcnt vmcnt(4)
	v_lshlrev_b32_e32 v46, 16, v44
	v_and_b32_e32 v47, 0xffff0000, v44
	v_lshlrev_b32_e32 v44, 16, v45
	v_and_b32_e32 v45, 0xffff0000, v45
	s_waitcnt lgkmcnt(0)
	v_pk_add_f32 v[40:41], v[40:41], v[46:47]
	v_pk_add_f32 v[42:43], v[42:43], v[44:45]
	v_cvt_pk_bf16_f32 v44, v40, v41
	v_cvt_pk_bf16_f32 v45, v42, v43
	s_cbranch_vccnz .LBB0_437
	v_lshl_add_u64 v[46:47], v[38:39], 0, v[0:1]
	s_mov_b64 s[2:3], 0
	global_store_dwordx2 v[46:47], v[44:45], off
